# loop-edge edit (strategy 9): GEMM K-loop back edge rotated, loop-control and next-iteration pointer SALU moved ahead of the loop-closing barrier
# baseline (speedup 1.0000x reference)
; #define PG8_STAGE(bufoff, gbase, voff) do { _Pragma("unroll") for (int _i = 0; _i < 2; ++_i) \
;         __builtin_amdgcn_global_load_lds((const unsigned*)((const char*)(gbase) + (voff)[_i]), (PG8_LAS unsigned*)(lds + (bufoff) + ldsw + _i * 8192), 16, 0, 0); } while (0)
; #define PG8_LDA(dst, b, h) do { _Pragma("unroll") for (int m = 0; m < 4; ++m) _Pragma("unroll") for (int k = 0; k < 2; ++k) dst[m][k] = *(const PG8_LAS bf16x8*)(lds + PG8_SA(b, h) + aoff + m * 2048 + k * 1024); } while (0)
; #define PG8_LDB(dst, b, h) do { _Pragma("unroll") for (int n = 0; n < 2; ++n) _Pragma("unroll") for (int k = 0; k < 2; ++k) dst[n][k] = *(const PG8_LAS bf16x8*)(lds + PG8_SB(b, h) + boff + n * 2048 + k * 1024); } while (0)
; #define PG8_MMA(ai, bj, At, Bt) do { __builtin_amdgcn_s_setprio(1); _Pragma("unroll") for (int m = 0; m < 4; ++m) _Pragma("unroll") for (int n = 0; n < 2; ++n) _Pragma("unroll") for (int k = 0; k < 2; ++k) \
;         acc[ai][bj][m][n] = __builtin_amdgcn_mfma_f32_16x16x32_bf16(Bt[n][k], At[m][k], acc[ai][bj][m][n], 0, 0, 0); __builtin_amdgcn_s_setprio(0); } while (0)
; #define PG8_WAIT_V(n) asm volatile("s_waitcnt vmcnt(" #n ")" ::: "memory")
; #define PG8_WAIT_L(n) asm volatile("s_waitcnt lgkmcnt(" #n ")" ::: "memory")
; template <class Epi, class Sched, bool ALIGN_EPI = false, bool SP2 = false>
; __device__ __forceinline__ void gemm_phase(PG8_LAS unsigned char* lds, const Gemm g, const Sched& S, const Epi& E) {
;     ...
;             const bool last = (t == nt - 2);
;             const char* a1 = cA + (size_t)(t + 1) * kstep;
;             const char* a2 = last ? nA : cA + (size_t)(t + 2) * kstep; const char* b2 = last ? nB : cB + (size_t)(t + 2) * kstep;
;             const char* a3 = a2 + kstep; const char* b3 = b2 + kstep;
;             if (last && has_next) S.a_ready(nxt);
;             if constexpr (SP2) {
;             PG8_LDB(B0, 0, 0); PG8_LDB(B1, 0, 1); PG8_SCHED; PG8_LDA(At, 0, 0); PG8_STAGE(PG8_SA(1, 1), a1 + hstep, voffA);
;             PG8_WAIT_V(8); PG8_WAIT_L(0); PG8_BAR; PG8_MMA(0, 0, At, B0); PG8_MMA(0, 1, At, B1); PG8_BAR; PG8_SCHED;
;             PG8_LDA(At, 0, 1); PG8_STAGE(PG8_SB(0, 0), b2, voffB); PG8_STAGE(PG8_SB(0, 1), b2 + hstep, voffB); PG8_STAGE(PG8_SA(0, 0), a2, voffA);
;             PG8_WAIT_V(8); PG8_WAIT_L(0); PG8_BAR; PG8_MMA(1, 0, At, B0); PG8_MMA(1, 1, At, B1); PG8_BAR; PG8_SCHED;
.LBB0_694:
	s_add_u32 s30, s28, 0xfffc0080
	s_addc_u32 s31, s29, -1
	s_add_i32 s46, 0, 0x10000
	s_cmp_eq_u32 s52, 12
	s_cselect_b32 s35, s21, s31
	s_cselect_b32 s34, vcc_lo, s30
	s_cselect_b32 s31, s19, s55
	s_cselect_b32 s30, vcc_hi, s54
	s_add_i32 s94, 0, 0x14000
.Lk694_body:
	v_add_u32_e32 v140, s46, v142
	ds_read_b128 v[146:149], v140
	ds_read_b128 v[150:153], v140 offset:1024
	ds_read_b128 v[154:157], v140 offset:2048
	ds_read_b128 v[158:161], v140 offset:3072
	v_add_u32_e32 v140, s94, v142
	ds_read_b128 v[162:165], v140
	ds_read_b128 v[166:169], v140 offset:1024
	ds_read_b128 v[170:173], v140 offset:2048
	ds_read_b128 v[174:177], v140 offset:3072
	v_lshl_add_u64 v[194:195], s[28:29], 0, v[136:137]
	s_add_i32 m0, s27, 0xc000
	ds_read_b128 v[178:181], v144
	ds_read_b128 v[182:185], v144 offset:1024
	ds_read_b128 v[186:189], v144 offset:2048
	ds_read_b128 v[190:193], v144 offset:3072
	ds_read_b128 v[204:207], v144 offset:4096
	ds_read_b128 v[208:211], v144 offset:5120
	ds_read_b128 v[212:215], v144 offset:6144
	ds_read_b128 v[216:219], v144 offset:7168
	global_load_lds_dwordx4 v[194:195], off
	v_lshl_add_u64 v[194:195], s[28:29], 0, v[138:139]
	s_add_i32 m0, s27, 0xe000
	s_nop 0
	global_load_lds_dwordx4 v[194:195], off
	s_waitcnt vmcnt(8)
	s_waitcnt lgkmcnt(0)
	s_barrier
	s_setprio 1
	s_waitcnt lgkmcnt(0)
	v_mfma_f32_16x16x32_bf16 v[128:131], v[146:149], v[178:181], v[128:131]
	v_mfma_f32_16x16x32_bf16 v[124:127], v[154:157], v[178:181], v[124:127]
	v_mfma_f32_16x16x32_bf16 v[116:119], v[146:149], v[186:189], v[116:119]
	v_mfma_f32_16x16x32_bf16 v[108:111], v[154:157], v[186:189], v[108:111]
	v_mfma_f32_16x16x32_bf16 v[100:103], v[146:149], v[204:207], v[100:103]
	v_mfma_f32_16x16x32_bf16 v[92:95], v[154:157], v[204:207], v[92:95]
	v_mfma_f32_16x16x32_bf16 v[84:87], v[146:149], v[212:215], v[84:87]
	v_mfma_f32_16x16x32_bf16 v[76:79], v[154:157], v[212:215], v[76:79]
	v_mfma_f32_16x16x32_bf16 v[128:131], v[150:153], v[182:185], v[128:131]
	v_mfma_f32_16x16x32_bf16 v[124:127], v[158:161], v[182:185], v[124:127]
	v_mfma_f32_16x16x32_bf16 v[116:119], v[150:153], v[190:193], v[116:119]
	v_mfma_f32_16x16x32_bf16 v[108:111], v[158:161], v[190:193], v[108:111]
	v_mfma_f32_16x16x32_bf16 v[100:103], v[150:153], v[208:211], v[100:103]
	v_mfma_f32_16x16x32_bf16 v[92:95], v[158:161], v[208:211], v[92:95]
	v_mfma_f32_16x16x32_bf16 v[84:87], v[150:153], v[216:219], v[84:87]
	v_mfma_f32_16x16x32_bf16 v[76:79], v[158:161], v[216:219], v[76:79]
	s_setprio 0
	s_setprio 1
	v_mfma_f32_16x16x32_bf16 v[120:123], v[162:165], v[178:181], v[120:123]
	v_mfma_f32_16x16x32_bf16 v[112:115], v[170:173], v[178:181], v[112:115]
	v_mfma_f32_16x16x32_bf16 v[104:107], v[162:165], v[186:189], v[104:107]
	v_mfma_f32_16x16x32_bf16 v[96:99], v[170:173], v[186:189], v[96:99]
	v_mfma_f32_16x16x32_bf16 v[88:91], v[162:165], v[204:207], v[88:91]
	v_mfma_f32_16x16x32_bf16 v[80:83], v[170:173], v[204:207], v[80:83]
	v_mfma_f32_16x16x32_bf16 v[72:75], v[162:165], v[212:215], v[72:75]
	v_mfma_f32_16x16x32_bf16 v[68:71], v[170:173], v[212:215], v[68:71]
	v_mfma_f32_16x16x32_bf16 v[120:123], v[166:169], v[182:185], v[120:123]
	v_mfma_f32_16x16x32_bf16 v[112:115], v[174:177], v[182:185], v[112:115]
	v_mfma_f32_16x16x32_bf16 v[104:107], v[166:169], v[190:193], v[104:107]
	v_mfma_f32_16x16x32_bf16 v[96:99], v[174:177], v[190:193], v[96:99]
	v_mfma_f32_16x16x32_bf16 v[88:91], v[166:169], v[208:211], v[88:91]
	v_mfma_f32_16x16x32_bf16 v[80:83], v[174:177], v[208:211], v[80:83]
	v_mfma_f32_16x16x32_bf16 v[72:75], v[166:169], v[216:219], v[72:75]
	v_mfma_f32_16x16x32_bf16 v[68:71], v[174:177], v[216:219], v[68:71]
	s_setprio 0
	s_barrier
	s_add_i32 s46, s46, s85
	v_lshl_add_u64 v[194:195], s[30:31], 0, v[2:3]
	s_mov_b32 m0, s46
	ds_read_b128 v[178:181], v144 offset:16384
	ds_read_b128 v[182:185], v144 offset:17408
	ds_read_b128 v[186:189], v144 offset:18432
	ds_read_b128 v[190:193], v144 offset:19456
	ds_read_b128 v[204:207], v144 offset:20480
	ds_read_b128 v[208:211], v144 offset:21504
	ds_read_b128 v[212:215], v144 offset:22528
	ds_read_b128 v[216:219], v144 offset:23552
	global_load_lds_dwordx4 v[194:195], off
	s_add_i32 m0, s46, 0x2000
	s_add_u32 s46, s30, 0x40000
	v_lshl_add_u64 v[236:237], s[30:31], 0, v[134:135]
	s_addc_u32 s47, s31, 0
	s_add_i32 s94, s94, s85
	global_load_lds_dwordx4 v[236:237], off
	v_lshl_add_u64 v[238:239], s[46:47], 0, v[2:3]
	s_mov_b32 m0, s94
	v_lshl_add_u64 v[240:241], s[34:35], 0, v[132:133]
	global_load_lds_dwordx4 v[238:239], off
	v_lshl_add_u64 v[238:239], s[46:47], 0, v[134:135]
	s_add_i32 m0, s94, 0x2000
	s_nop 0
	global_load_lds_dwordx4 v[238:239], off
	v_lshl_add_u64 v[238:239], s[34:35], 0, v[0:1]
	s_mov_b32 m0, s27
	s_nop 0
	global_load_lds_dwordx4 v[238:239], off
	s_mov_b32 m0, s68
	s_nop 0
	global_load_lds_dwordx4 v[240:241], off
	s_waitcnt vmcnt(8)
	s_waitcnt lgkmcnt(0)
	s_barrier
; #define PG8_STAGE(bufoff, gbase, voff) do { _Pragma("unroll") for (int _i = 0; _i < 2; ++_i) \
;         __builtin_amdgcn_global_load_lds((const unsigned*)((const char*)(gbase) + (voff)[_i]), (PG8_LAS unsigned*)(lds + (bufoff) + ldsw + _i * 8192), 16, 0, 0); } while (0)
; #define PG8_LDA(dst, b, h) do { _Pragma("unroll") for (int m = 0; m < 4; ++m) _Pragma("unroll") for (int k = 0; k < 2; ++k) dst[m][k] = *(const PG8_LAS bf16x8*)(lds + PG8_SA(b, h) + aoff + m * 2048 + k * 1024); } while (0)
; #define PG8_LDB(dst, b, h) do { _Pragma("unroll") for (int n = 0; n < 2; ++n) _Pragma("unroll") for (int k = 0; k < 2; ++k) dst[n][k] = *(const PG8_LAS bf16x8*)(lds + PG8_SB(b, h) + boff + n * 2048 + k * 1024); } while (0)
; #define PG8_MMA(ai, bj, At, Bt) do { __builtin_amdgcn_s_setprio(1); _Pragma("unroll") for (int m = 0; m < 4; ++m) _Pragma("unroll") for (int n = 0; n < 2; ++n) _Pragma("unroll") for (int k = 0; k < 2; ++k) \
;         acc[ai][bj][m][n] = __builtin_amdgcn_mfma_f32_16x16x32_bf16(Bt[n][k], At[m][k], acc[ai][bj][m][n], 0, 0, 0); __builtin_amdgcn_s_setprio(0); } while (0)
; #define PG8_WAIT_V(n) asm volatile("s_waitcnt vmcnt(" #n ")" ::: "memory")
; #define PG8_WAIT_L(n) asm volatile("s_waitcnt lgkmcnt(" #n ")" ::: "memory")
; #define PG8_BAR __builtin_amdgcn_s_barrier()
; #define PG8_SCHED __builtin_amdgcn_sched_barrier(0)
; template <class Epi, class Sched, bool ALIGN_EPI = false, bool SP2 = false>
; __device__ __forceinline__ void gemm_phase(PG8_LAS unsigned char* lds, const Gemm g, const Sched& S, const Epi& E) {
;     ...
;             PG8_WAIT_V(8); PG8_WAIT_L(0); PG8_BAR; PG8_MMA(1, 0, At, B0); PG8_MMA(1, 1, At, B1); PG8_BAR; PG8_SCHED;
;             PG8_LDB(B0, 1, 0); PG8_LDB(B1, 1, 1); PG8_SCHED; PG8_LDA(At, 1, 0); PG8_STAGE(PG8_SA(0, 1), a2 + hstep, voffA);
;             PG8_WAIT_V(8); PG8_WAIT_L(0); PG8_BAR; PG8_MMA(0, 0, At, B0); PG8_MMA(0, 1, At, B1); PG8_BAR; PG8_SCHED;
	s_setprio 1
	s_waitcnt lgkmcnt(0)
	v_mfma_f32_16x16x32_bf16 v[64:67], v[146:149], v[178:181], v[64:67]
	v_mfma_f32_16x16x32_bf16 v[60:63], v[154:157], v[178:181], v[60:63]
	v_mfma_f32_16x16x32_bf16 v[52:55], v[146:149], v[186:189], v[52:55]
	v_mfma_f32_16x16x32_bf16 v[44:47], v[154:157], v[186:189], v[44:47]
	v_mfma_f32_16x16x32_bf16 v[36:39], v[146:149], v[204:207], v[36:39]
	v_mfma_f32_16x16x32_bf16 v[28:31], v[154:157], v[204:207], v[28:31]
	v_mfma_f32_16x16x32_bf16 v[20:23], v[146:149], v[212:215], v[20:23]
	v_mfma_f32_16x16x32_bf16 v[12:15], v[154:157], v[212:215], v[12:15]
	v_mfma_f32_16x16x32_bf16 v[64:67], v[150:153], v[182:185], v[64:67]
	v_mfma_f32_16x16x32_bf16 v[60:63], v[158:161], v[182:185], v[60:63]
	v_mfma_f32_16x16x32_bf16 v[52:55], v[150:153], v[190:193], v[52:55]
	v_mfma_f32_16x16x32_bf16 v[44:47], v[158:161], v[190:193], v[44:47]
	v_mfma_f32_16x16x32_bf16 v[36:39], v[150:153], v[208:211], v[36:39]
	v_mfma_f32_16x16x32_bf16 v[28:31], v[158:161], v[208:211], v[28:31]
	v_mfma_f32_16x16x32_bf16 v[20:23], v[150:153], v[216:219], v[20:23]
	v_mfma_f32_16x16x32_bf16 v[12:15], v[158:161], v[216:219], v[12:15]
	s_setprio 0
	s_setprio 1
	v_mfma_f32_16x16x32_bf16 v[56:59], v[162:165], v[178:181], v[56:59]
	v_mfma_f32_16x16x32_bf16 v[48:51], v[170:173], v[178:181], v[48:51]
	v_mfma_f32_16x16x32_bf16 v[40:43], v[162:165], v[186:189], v[40:43]
	v_mfma_f32_16x16x32_bf16 v[32:35], v[170:173], v[186:189], v[32:35]
	v_mfma_f32_16x16x32_bf16 v[24:27], v[162:165], v[204:207], v[24:27]
	v_mfma_f32_16x16x32_bf16 v[16:19], v[170:173], v[204:207], v[16:19]
	v_mfma_f32_16x16x32_bf16 v[8:11], v[162:165], v[212:215], v[8:11]
	v_mfma_f32_16x16x32_bf16 v[4:7], v[170:173], v[212:215], v[4:7]
	v_mfma_f32_16x16x32_bf16 v[56:59], v[166:169], v[182:185], v[56:59]
	v_mfma_f32_16x16x32_bf16 v[48:51], v[174:177], v[182:185], v[48:51]
	v_mfma_f32_16x16x32_bf16 v[40:43], v[166:169], v[190:193], v[40:43]
	v_mfma_f32_16x16x32_bf16 v[32:35], v[174:177], v[190:193], v[32:35]
	v_mfma_f32_16x16x32_bf16 v[24:27], v[166:169], v[208:211], v[24:27]
	v_mfma_f32_16x16x32_bf16 v[16:19], v[174:177], v[208:211], v[16:19]
	v_mfma_f32_16x16x32_bf16 v[8:11], v[166:169], v[216:219], v[8:11]
	v_mfma_f32_16x16x32_bf16 v[4:7], v[174:177], v[216:219], v[4:7]
	s_setprio 0
	s_barrier
	s_add_i32 s46, 0, 0x18000
	v_add_u32_e32 v140, s46, v142
	s_add_i32 s47, 0, 0x1c000
	ds_read_b128 v[146:149], v140
	ds_read_b128 v[150:153], v140 offset:1024
	ds_read_b128 v[154:157], v140 offset:2048
	ds_read_b128 v[158:161], v140 offset:3072
	v_add_u32_e32 v140, s47, v142
	ds_read_b128 v[162:165], v140
	ds_read_b128 v[166:169], v140 offset:1024
	ds_read_b128 v[170:173], v140 offset:2048
	ds_read_b128 v[174:177], v140 offset:3072
	s_add_u32 s34, s34, 0x40000
	s_addc_u32 s35, s35, 0
	s_mov_b32 m0, s69
	v_lshl_add_u64 v[242:243], s[34:35], 0, v[0:1]
	ds_read_b128 v[178:181], v144 offset:32768
	ds_read_b128 v[182:185], v144 offset:33792
	ds_read_b128 v[186:189], v144 offset:34816
	ds_read_b128 v[190:193], v144 offset:35840
	ds_read_b128 v[204:207], v144 offset:36864
	ds_read_b128 v[208:211], v144 offset:37888
	ds_read_b128 v[212:215], v144 offset:38912
	ds_read_b128 v[216:219], v144 offset:39936
	global_load_lds_dwordx4 v[242:243], off
	v_lshl_add_u64 v[242:243], s[34:35], 0, v[132:133]
	s_mov_b32 m0, s33
	s_nop 0
	global_load_lds_dwordx4 v[242:243], off
	s_waitcnt vmcnt(8)
	s_waitcnt lgkmcnt(0)
	s_barrier
	s_setprio 1
	s_waitcnt lgkmcnt(0)
	v_mfma_f32_16x16x32_bf16 v[128:131], v[146:149], v[178:181], v[128:131]
	v_mfma_f32_16x16x32_bf16 v[124:127], v[154:157], v[178:181], v[124:127]
	v_mfma_f32_16x16x32_bf16 v[116:119], v[146:149], v[186:189], v[116:119]
	v_mfma_f32_16x16x32_bf16 v[108:111], v[154:157], v[186:189], v[108:111]
	v_mfma_f32_16x16x32_bf16 v[100:103], v[146:149], v[204:207], v[100:103]
	v_mfma_f32_16x16x32_bf16 v[92:95], v[154:157], v[204:207], v[92:95]
	v_mfma_f32_16x16x32_bf16 v[84:87], v[146:149], v[212:215], v[84:87]
	v_mfma_f32_16x16x32_bf16 v[76:79], v[154:157], v[212:215], v[76:79]
	v_mfma_f32_16x16x32_bf16 v[128:131], v[150:153], v[182:185], v[128:131]
	v_mfma_f32_16x16x32_bf16 v[124:127], v[158:161], v[182:185], v[124:127]
	v_mfma_f32_16x16x32_bf16 v[116:119], v[150:153], v[190:193], v[116:119]
	v_mfma_f32_16x16x32_bf16 v[108:111], v[158:161], v[190:193], v[108:111]
	v_mfma_f32_16x16x32_bf16 v[100:103], v[150:153], v[208:211], v[100:103]
	v_mfma_f32_16x16x32_bf16 v[92:95], v[158:161], v[208:211], v[92:95]
	v_mfma_f32_16x16x32_bf16 v[84:87], v[150:153], v[216:219], v[84:87]
	v_mfma_f32_16x16x32_bf16 v[76:79], v[158:161], v[216:219], v[76:79]
	s_setprio 0
	s_setprio 1
	v_mfma_f32_16x16x32_bf16 v[120:123], v[162:165], v[178:181], v[120:123]
	v_mfma_f32_16x16x32_bf16 v[112:115], v[170:173], v[178:181], v[112:115]
	v_mfma_f32_16x16x32_bf16 v[104:107], v[162:165], v[186:189], v[104:107]
	v_mfma_f32_16x16x32_bf16 v[96:99], v[170:173], v[186:189], v[96:99]
	v_mfma_f32_16x16x32_bf16 v[88:91], v[162:165], v[204:207], v[88:91]
	v_mfma_f32_16x16x32_bf16 v[80:83], v[170:173], v[204:207], v[80:83]
	v_mfma_f32_16x16x32_bf16 v[72:75], v[162:165], v[212:215], v[72:75]
	v_mfma_f32_16x16x32_bf16 v[68:71], v[170:173], v[212:215], v[68:71]
	v_mfma_f32_16x16x32_bf16 v[120:123], v[166:169], v[182:185], v[120:123]
	v_mfma_f32_16x16x32_bf16 v[112:115], v[174:177], v[182:185], v[112:115]
	v_mfma_f32_16x16x32_bf16 v[104:107], v[166:169], v[190:193], v[104:107]
	v_mfma_f32_16x16x32_bf16 v[96:99], v[174:177], v[190:193], v[96:99]
	v_mfma_f32_16x16x32_bf16 v[88:91], v[166:169], v[208:211], v[88:91]
	v_mfma_f32_16x16x32_bf16 v[80:83], v[174:177], v[208:211], v[80:83]
	v_mfma_f32_16x16x32_bf16 v[72:75], v[166:169], v[216:219], v[72:75]
	v_mfma_f32_16x16x32_bf16 v[68:71], v[174:177], v[216:219], v[68:71]
	s_setprio 0
	s_barrier
; #define PG8_STAGE(bufoff, gbase, voff) do { _Pragma("unroll") for (int _i = 0; _i < 2; ++_i) \
;         __builtin_amdgcn_global_load_lds((const unsigned*)((const char*)(gbase) + (voff)[_i]), (PG8_LAS unsigned*)(lds + (bufoff) + ldsw + _i * 8192), 16, 0, 0); } while (0)
; #define PG8_LDA(dst, b, h) do { _Pragma("unroll") for (int m = 0; m < 4; ++m) _Pragma("unroll") for (int k = 0; k < 2; ++k) dst[m][k] = *(const PG8_LAS bf16x8*)(lds + PG8_SA(b, h) + aoff + m * 2048 + k * 1024); } while (0)
; #define PG8_MMA(ai, bj, At, Bt) do { __builtin_amdgcn_s_setprio(1); _Pragma("unroll") for (int m = 0; m < 4; ++m) _Pragma("unroll") for (int n = 0; n < 2; ++n) _Pragma("unroll") for (int k = 0; k < 2; ++k) \
;         acc[ai][bj][m][n] = __builtin_amdgcn_mfma_f32_16x16x32_bf16(Bt[n][k], At[m][k], acc[ai][bj][m][n], 0, 0, 0); __builtin_amdgcn_s_setprio(0); } while (0)
; #define PG8_WAIT_V(n) asm volatile("s_waitcnt vmcnt(" #n ")" ::: "memory")
; #define PG8_WAIT_L(n) asm volatile("s_waitcnt lgkmcnt(" #n ")" ::: "memory")
; #define PG8_BAR __builtin_amdgcn_s_barrier()
; #define PG8_SCHED __builtin_amdgcn_sched_barrier(0)
; template <class Epi, class Sched, bool ALIGN_EPI = false, bool SP2 = false>
; __device__ __forceinline__ void gemm_phase(PG8_LAS unsigned char* lds, const Gemm g, const Sched& S, const Epi& E) {
;     ...
;         for (int t = 0; t < nt; t += 2) {
;             const bool last = (t == nt - 2);
;             const char* a1 = cA + (size_t)(t + 1) * kstep;
;             const char* a2 = last ? nA : cA + (size_t)(t + 2) * kstep; const char* b2 = last ? nB : cB + (size_t)(t + 2) * kstep;
;             const char* a3 = a2 + kstep; const char* b3 = b2 + kstep;
;     ...
;             PG8_LDA(At, 1, 1); PG8_STAGE(PG8_SB(1, 0), b3, voffB); PG8_STAGE(PG8_SB(1, 1), b3 + hstep, voffB); PG8_STAGE(PG8_SA(1, 0), a3, voffA);
;             PG8_WAIT_V(8); PG8_WAIT_L(0); PG8_BAR; PG8_MMA(1, 0, At, B0); PG8_MMA(1, 1, At, B1); PG8_BAR; PG8_SCHED;
	s_add_i32 s34, s46, s85
	v_lshl_add_u64 v[194:195], v[194:195], 0, s[42:43]
	s_mov_b32 m0, s34
	ds_read_b128 v[178:181], v144 offset:49152
	ds_read_b128 v[182:185], v144 offset:50176
	ds_read_b128 v[186:189], v144 offset:51200
	ds_read_b128 v[190:193], v144 offset:52224
	ds_read_b128 v[204:207], v144 offset:53248
	ds_read_b128 v[208:211], v144 offset:54272
	ds_read_b128 v[212:215], v144 offset:55296
	ds_read_b128 v[216:219], v144 offset:56320
	global_load_lds_dwordx4 v[194:195], off
	s_add_i32 m0, s34, 0x2000
	s_add_u32 s30, s30, 0x40080
	v_lshl_add_u64 v[194:195], v[236:237], 0, s[42:43]
	s_addc_u32 s31, s31, 0
	s_add_i32 s34, s47, s85
	global_load_lds_dwordx4 v[194:195], off
	v_lshl_add_u64 v[194:195], s[30:31], 0, v[2:3]
	s_mov_b32 m0, s34
	s_nop 0
	global_load_lds_dwordx4 v[194:195], off
	v_lshl_add_u64 v[194:195], s[30:31], 0, v[134:135]
	s_add_i32 m0, s34, 0x2000
	s_nop 0
	global_load_lds_dwordx4 v[194:195], off
	v_lshl_add_u64 v[194:195], v[238:239], 0, s[42:43]
	s_mov_b32 m0, s66
	s_nop 0
	global_load_lds_dwordx4 v[194:195], off
	v_lshl_add_u64 v[194:195], v[240:241], 0, s[42:43]
	s_mov_b32 m0, s67
	s_nop 0
	global_load_lds_dwordx4 v[194:195], off
	s_waitcnt vmcnt(8)
	s_waitcnt lgkmcnt(0)
	s_barrier
	s_setprio 1
	s_waitcnt lgkmcnt(0)
	v_mfma_f32_16x16x32_bf16 v[64:67], v[146:149], v[178:181], v[64:67]
	v_mfma_f32_16x16x32_bf16 v[60:63], v[154:157], v[178:181], v[60:63]
	v_mfma_f32_16x16x32_bf16 v[52:55], v[146:149], v[186:189], v[52:55]
	v_mfma_f32_16x16x32_bf16 v[44:47], v[154:157], v[186:189], v[44:47]
	v_mfma_f32_16x16x32_bf16 v[36:39], v[146:149], v[204:207], v[36:39]
	v_mfma_f32_16x16x32_bf16 v[28:31], v[154:157], v[204:207], v[28:31]
	v_mfma_f32_16x16x32_bf16 v[20:23], v[146:149], v[212:215], v[20:23]
	v_mfma_f32_16x16x32_bf16 v[12:15], v[154:157], v[212:215], v[12:15]
	v_mfma_f32_16x16x32_bf16 v[64:67], v[150:153], v[182:185], v[64:67]
	v_mfma_f32_16x16x32_bf16 v[60:63], v[158:161], v[182:185], v[60:63]
	v_mfma_f32_16x16x32_bf16 v[52:55], v[150:153], v[190:193], v[52:55]
	v_mfma_f32_16x16x32_bf16 v[44:47], v[158:161], v[190:193], v[44:47]
	v_mfma_f32_16x16x32_bf16 v[36:39], v[150:153], v[208:211], v[36:39]
	v_mfma_f32_16x16x32_bf16 v[28:31], v[158:161], v[208:211], v[28:31]
	v_mfma_f32_16x16x32_bf16 v[20:23], v[150:153], v[216:219], v[20:23]
	v_mfma_f32_16x16x32_bf16 v[12:15], v[158:161], v[216:219], v[12:15]
	s_setprio 0
	s_setprio 1
	v_mfma_f32_16x16x32_bf16 v[56:59], v[162:165], v[178:181], v[56:59]
	v_mfma_f32_16x16x32_bf16 v[48:51], v[170:173], v[178:181], v[48:51]
	v_mfma_f32_16x16x32_bf16 v[40:43], v[162:165], v[186:189], v[40:43]
	v_mfma_f32_16x16x32_bf16 v[32:35], v[170:173], v[186:189], v[32:35]
	v_mfma_f32_16x16x32_bf16 v[24:27], v[162:165], v[204:207], v[24:27]
	v_mfma_f32_16x16x32_bf16 v[16:19], v[170:173], v[204:207], v[16:19]
	v_mfma_f32_16x16x32_bf16 v[8:11], v[162:165], v[212:215], v[8:11]
	v_mfma_f32_16x16x32_bf16 v[4:7], v[170:173], v[212:215], v[4:7]
	v_mfma_f32_16x16x32_bf16 v[56:59], v[166:169], v[182:185], v[56:59]
	v_mfma_f32_16x16x32_bf16 v[48:51], v[174:177], v[182:185], v[48:51]
	v_mfma_f32_16x16x32_bf16 v[40:43], v[166:169], v[190:193], v[40:43]
	v_mfma_f32_16x16x32_bf16 v[32:35], v[174:177], v[190:193], v[32:35]
	v_mfma_f32_16x16x32_bf16 v[24:27], v[166:169], v[208:211], v[24:27]
	v_mfma_f32_16x16x32_bf16 v[16:19], v[174:177], v[208:211], v[16:19]
	v_mfma_f32_16x16x32_bf16 v[8:11], v[166:169], v[216:219], v[8:11]
	v_mfma_f32_16x16x32_bf16 v[4:7], v[174:177], v[216:219], v[4:7]
	s_setprio 0
	s_add_i32 s52, s52, 2
	s_add_u32 s28, s28, 0x100
	s_addc_u32 s29, s29, 0
	s_add_u32 s54, s54, 0x100
	s_addc_u32 s55, s55, 0
	s_cmp_gt_u32 s52, 13
	s_cbranch_scc1 .Lk694_exit
	s_add_u32 s30, s28, 0xfffc0080
	s_addc_u32 s31, s29, -1
	s_add_i32 s46, 0, 0x10000
	s_cmp_eq_u32 s52, 12
	s_cselect_b32 s35, s21, s31
	s_cselect_b32 s34, vcc_lo, s30
	s_cselect_b32 s31, s19, s55
	s_cselect_b32 s30, vcc_hi, s54
	s_add_i32 s94, 0, 0x14000
	s_barrier
	s_branch .Lk694_body
.Lk694_exit:
	s_barrier
	s_and_b64 vcc, exec, s[16:17]
	s_cbranch_vccz .LBB0_697
	s_barrier

; #define PG8_STAGE(bufoff, gbase, voff) do { _Pragma("unroll") for (int _i = 0; _i < 2; ++_i) \
;         __builtin_amdgcn_global_load_lds((const unsigned*)((const char*)(gbase) + (voff)[_i]), (PG8_LAS unsigned*)(lds + (bufoff) + ldsw + _i * 8192), 16, 0, 0); } while (0)
; #define PG8_LDA(dst, b, h) do { _Pragma("unroll") for (int m = 0; m < 4; ++m) _Pragma("unroll") for (int k = 0; k < 2; ++k) dst[m][k] = *(const PG8_LAS bf16x8*)(lds + PG8_SA(b, h) + aoff + m * 2048 + k * 1024); } while (0)
; #define PG8_LDB(dst, b, h) do { _Pragma("unroll") for (int n = 0; n < 2; ++n) _Pragma("unroll") for (int k = 0; k < 2; ++k) dst[n][k] = *(const PG8_LAS bf16x8*)(lds + PG8_SB(b, h) + boff + n * 2048 + k * 1024); } while (0)
; #define PG8_MMA(ai, bj, At, Bt) do { __builtin_amdgcn_s_setprio(1); _Pragma("unroll") for (int m = 0; m < 4; ++m) _Pragma("unroll") for (int n = 0; n < 2; ++n) _Pragma("unroll") for (int k = 0; k < 2; ++k) \
;         acc[ai][bj][m][n] = __builtin_amdgcn_mfma_f32_16x16x32_bf16(Bt[n][k], At[m][k], acc[ai][bj][m][n], 0, 0, 0); __builtin_amdgcn_s_setprio(0); } while (0)
; #define PG8_WAIT_V(n) asm volatile("s_waitcnt vmcnt(" #n ")" ::: "memory")
; #define PG8_WAIT_L(n) asm volatile("s_waitcnt lgkmcnt(" #n ")" ::: "memory")
; template <class Epi, class Sched, bool ALIGN_EPI = false, bool SP2 = false>
; __device__ __forceinline__ void gemm_phase(PG8_LAS unsigned char* lds, const Gemm g, const Sched& S, const Epi& E) {
;     ...
;             const bool last = (t == nt - 2);
;             const char* a1 = cA + (size_t)(t + 1) * kstep;
;             const char* a2 = last ? nA : cA + (size_t)(t + 2) * kstep; const char* b2 = last ? nB : cB + (size_t)(t + 2) * kstep;
;             const char* a3 = a2 + kstep; const char* b3 = b2 + kstep;
;             if (last && has_next) S.a_ready(nxt);
;             if constexpr (SP2) {
;             PG8_LDB(B0, 0, 0); PG8_LDB(B1, 0, 1); PG8_SCHED; PG8_LDA(At, 0, 0); PG8_STAGE(PG8_SA(1, 1), a1 + hstep, voffA);
;             PG8_WAIT_V(8); PG8_WAIT_L(0); PG8_BAR; PG8_MMA(0, 0, At, B0); PG8_MMA(0, 1, At, B1); PG8_BAR; PG8_SCHED;
;             PG8_LDA(At, 0, 1); PG8_STAGE(PG8_SB(0, 0), b2, voffB); PG8_STAGE(PG8_SB(0, 1), b2 + hstep, voffB); PG8_STAGE(PG8_SA(0, 0), a2, voffA);
;             PG8_WAIT_V(8); PG8_WAIT_L(0); PG8_BAR; PG8_MMA(1, 0, At, B0); PG8_MMA(1, 1, At, B1); PG8_BAR; PG8_SCHED;
.LBB0_720:
	s_add_i32 s40, s20, 2
	s_add_u32 s41, s12, s18
	s_addc_u32 s21, s13, s19
	s_add_u32 s46, s8, s18
	s_addc_u32 s47, s9, s19
	s_add_i32 s52, 0, 0x10000
	s_cmp_eq_u32 s78, s20
	s_cselect_b32 s21, s1, s21
	s_cselect_b32 s20, s0, s41
	s_cselect_b32 s49, s15, s47
	s_cselect_b32 s48, s14, s46
	s_add_i32 s41, 0, 0x14000
.Lk720_body:
	v_add_u32_e32 v134, s52, v120
	ds_read_b128 v[122:125], v134
	ds_read_b128 v[126:129], v134 offset:1024
	ds_read_b128 v[130:133], v134 offset:2048
	ds_read_b128 v[140:143], v134 offset:3072
	v_add_u32_e32 v134, s41, v120
	ds_read_b128 v[164:167], v134
	ds_read_b128 v[168:171], v134 offset:1024
	ds_read_b128 v[172:175], v134 offset:2048
	ds_read_b128 v[176:179], v134 offset:3072
	v_lshl_add_u64 v[134:135], s[12:13], 0, v[110:111]
	s_add_i32 m0, s23, 0xc000
	ds_read_b128 v[180:183], v121
	ds_read_b128 v[184:187], v121 offset:1024
	ds_read_b128 v[188:191], v121 offset:2048
	ds_read_b128 v[192:195], v121 offset:3072
	ds_read_b128 v[208:211], v121 offset:4096
	ds_read_b128 v[212:215], v121 offset:5120
	ds_read_b128 v[236:239], v121 offset:6144
	ds_read_b128 v[240:243], v121 offset:7168
	global_load_lds_dwordx4 v[134:135], off
	v_lshl_add_u64 v[134:135], s[12:13], 0, v[108:109]
	s_add_i32 m0, s23, 0xe000
	s_nop 0
	global_load_lds_dwordx4 v[134:135], off
	s_waitcnt vmcnt(8)
	s_waitcnt lgkmcnt(0)
	s_barrier
	s_setprio 1
	s_waitcnt lgkmcnt(0)
	v_mfma_f32_16x16x32_bf16 v[96:99], v[122:125], v[180:183], v[96:99]
	v_mfma_f32_16x16x32_bf16 v[160:163], v[130:133], v[180:183], v[160:163]
	v_mfma_f32_16x16x32_bf16 v[88:91], v[122:125], v[188:191], v[88:91]
	v_mfma_f32_16x16x32_bf16 v[156:159], v[130:133], v[188:191], v[156:159]
	v_mfma_f32_16x16x32_bf16 v[92:95], v[122:125], v[208:211], v[92:95]
	v_mfma_f32_16x16x32_bf16 v[152:155], v[130:133], v[208:211], v[152:155]
	v_mfma_f32_16x16x32_bf16 v[72:75], v[122:125], v[236:239], v[72:75]
	v_mfma_f32_16x16x32_bf16 v[148:151], v[130:133], v[236:239], v[148:151]
	v_mfma_f32_16x16x32_bf16 v[96:99], v[126:129], v[184:187], v[96:99]
	v_mfma_f32_16x16x32_bf16 v[160:163], v[140:143], v[184:187], v[160:163]
	v_mfma_f32_16x16x32_bf16 v[88:91], v[126:129], v[192:195], v[88:91]
	v_mfma_f32_16x16x32_bf16 v[156:159], v[140:143], v[192:195], v[156:159]
	v_mfma_f32_16x16x32_bf16 v[92:95], v[126:129], v[212:215], v[92:95]
	v_mfma_f32_16x16x32_bf16 v[152:155], v[140:143], v[212:215], v[152:155]
	v_mfma_f32_16x16x32_bf16 v[72:75], v[126:129], v[240:243], v[72:75]
	v_mfma_f32_16x16x32_bf16 v[148:151], v[140:143], v[240:243], v[148:151]
	s_setprio 0
	s_setprio 1
	v_mfma_f32_16x16x32_bf16 v[84:87], v[164:167], v[180:183], v[84:87]
	v_mfma_f32_16x16x32_bf16 v[32:35], v[172:175], v[180:183], v[32:35]
	v_mfma_f32_16x16x32_bf16 v[76:79], v[164:167], v[188:191], v[76:79]
	v_mfma_f32_16x16x32_bf16 v[28:31], v[172:175], v[188:191], v[28:31]
	v_mfma_f32_16x16x32_bf16 v[60:63], v[164:167], v[208:211], v[60:63]
	v_mfma_f32_16x16x32_bf16 v[24:27], v[172:175], v[208:211], v[24:27]
	v_mfma_f32_16x16x32_bf16 v[56:59], v[164:167], v[236:239], v[56:59]
	v_mfma_f32_16x16x32_bf16 v[20:23], v[172:175], v[236:239], v[20:23]
	v_mfma_f32_16x16x32_bf16 v[84:87], v[168:171], v[184:187], v[84:87]
	v_mfma_f32_16x16x32_bf16 v[32:35], v[176:179], v[184:187], v[32:35]
	v_mfma_f32_16x16x32_bf16 v[76:79], v[168:171], v[192:195], v[76:79]
	v_mfma_f32_16x16x32_bf16 v[28:31], v[176:179], v[192:195], v[28:31]
	v_mfma_f32_16x16x32_bf16 v[60:63], v[168:171], v[212:215], v[60:63]
	v_mfma_f32_16x16x32_bf16 v[24:27], v[176:179], v[212:215], v[24:27]
	v_mfma_f32_16x16x32_bf16 v[56:59], v[168:171], v[240:243], v[56:59]
	v_mfma_f32_16x16x32_bf16 v[20:23], v[176:179], v[240:243], v[20:23]
	s_setprio 0
	s_barrier
	s_add_i32 s46, s52, s22
	v_lshl_add_u64 v[204:205], s[48:49], 0, v[2:3]
	s_mov_b32 m0, s46
	ds_read_b128 v[180:183], v121 offset:16384
	ds_read_b128 v[184:187], v121 offset:17408
	ds_read_b128 v[188:191], v121 offset:18432
	ds_read_b128 v[192:195], v121 offset:19456
	ds_read_b128 v[208:211], v121 offset:20480
	ds_read_b128 v[212:215], v121 offset:21504
	ds_read_b128 v[236:239], v121 offset:22528
	ds_read_b128 v[240:243], v121 offset:23552
	global_load_lds_dwordx4 v[204:205], off
	s_add_i32 m0, s46, 0x2000
	v_lshl_add_u64 v[216:217], s[48:49], 0, v[0:1]
	s_add_u32 s48, s48, s77
	s_addc_u32 s49, s49, 0
	s_add_i32 s41, s41, s22
	global_load_lds_dwordx4 v[216:217], off
	v_lshl_add_u64 v[244:245], s[48:49], 0, v[2:3]
	s_mov_b32 m0, s41
	v_lshl_add_u64 v[246:247], s[48:49], 0, v[0:1]
	global_load_lds_dwordx4 v[244:245], off
	s_add_i32 m0, s41, 0x2000
	v_lshl_add_u64 v[248:249], s[20:21], 0, v[102:103]
	global_load_lds_dwordx4 v[246:247], off
	s_mov_b32 m0, s23
	v_lshl_add_u64 v[250:251], s[20:21], 0, v[100:101]
	global_load_lds_dwordx4 v[248:249], off
	s_mov_b32 m0, s24
	s_nop 0
	global_load_lds_dwordx4 v[250:251], off
	s_waitcnt vmcnt(8)
	s_waitcnt lgkmcnt(0)
	s_barrier
; #define PG8_STAGE(bufoff, gbase, voff) do { _Pragma("unroll") for (int _i = 0; _i < 2; ++_i) \
;         __builtin_amdgcn_global_load_lds((const unsigned*)((const char*)(gbase) + (voff)[_i]), (PG8_LAS unsigned*)(lds + (bufoff) + ldsw + _i * 8192), 16, 0, 0); } while (0)
; #define PG8_LDA(dst, b, h) do { _Pragma("unroll") for (int m = 0; m < 4; ++m) _Pragma("unroll") for (int k = 0; k < 2; ++k) dst[m][k] = *(const PG8_LAS bf16x8*)(lds + PG8_SA(b, h) + aoff + m * 2048 + k * 1024); } while (0)
; #define PG8_LDB(dst, b, h) do { _Pragma("unroll") for (int n = 0; n < 2; ++n) _Pragma("unroll") for (int k = 0; k < 2; ++k) dst[n][k] = *(const PG8_LAS bf16x8*)(lds + PG8_SB(b, h) + boff + n * 2048 + k * 1024); } while (0)
; #define PG8_MMA(ai, bj, At, Bt) do { __builtin_amdgcn_s_setprio(1); _Pragma("unroll") for (int m = 0; m < 4; ++m) _Pragma("unroll") for (int n = 0; n < 2; ++n) _Pragma("unroll") for (int k = 0; k < 2; ++k) \
;         acc[ai][bj][m][n] = __builtin_amdgcn_mfma_f32_16x16x32_bf16(Bt[n][k], At[m][k], acc[ai][bj][m][n], 0, 0, 0); __builtin_amdgcn_s_setprio(0); } while (0)
; #define PG8_WAIT_V(n) asm volatile("s_waitcnt vmcnt(" #n ")" ::: "memory")
; #define PG8_WAIT_L(n) asm volatile("s_waitcnt lgkmcnt(" #n ")" ::: "memory")
; #define PG8_BAR __builtin_amdgcn_s_barrier()
; #define PG8_SCHED __builtin_amdgcn_sched_barrier(0)
; template <class Epi, class Sched, bool ALIGN_EPI = false, bool SP2 = false>
; __device__ __forceinline__ void gemm_phase(PG8_LAS unsigned char* lds, const Gemm g, const Sched& S, const Epi& E) {
;     ...
;             PG8_WAIT_V(8); PG8_WAIT_L(0); PG8_BAR; PG8_MMA(1, 0, At, B0); PG8_MMA(1, 1, At, B1); PG8_BAR; PG8_SCHED;
;             PG8_LDB(B0, 1, 0); PG8_LDB(B1, 1, 1); PG8_SCHED; PG8_LDA(At, 1, 0); PG8_STAGE(PG8_SA(0, 1), a2 + hstep, voffA);
;             PG8_WAIT_V(8); PG8_WAIT_L(0); PG8_BAR; PG8_MMA(0, 0, At, B0); PG8_MMA(0, 1, At, B1); PG8_BAR; PG8_SCHED;
	s_setprio 1
	s_waitcnt lgkmcnt(0)
	v_mfma_f32_16x16x32_bf16 v[80:83], v[122:125], v[180:183], v[80:83]
	v_mfma_f32_16x16x32_bf16 v[144:147], v[130:133], v[180:183], v[144:147]
	v_mfma_f32_16x16x32_bf16 v[64:67], v[122:125], v[188:191], v[64:67]
	v_mfma_f32_16x16x32_bf16 v[134:137], v[130:133], v[188:191], v[136:139]
	v_mfma_f32_16x16x32_bf16 v[68:71], v[122:125], v[208:211], v[68:71]
	v_mfma_f32_16x16x32_bf16 v[116:119], v[130:133], v[208:211], v[116:119]
	v_mfma_f32_16x16x32_bf16 v[52:55], v[122:125], v[236:239], v[52:55]
	v_mfma_f32_16x16x32_bf16 v[112:115], v[130:133], v[236:239], v[112:115]
	v_mfma_f32_16x16x32_bf16 v[80:83], v[126:129], v[184:187], v[80:83]
	v_mfma_f32_16x16x32_bf16 v[144:147], v[140:143], v[184:187], v[144:147]
	v_mfma_f32_16x16x32_bf16 v[64:67], v[126:129], v[192:195], v[64:67]
	v_mfma_f32_16x16x32_bf16 v[134:137], v[140:143], v[192:195], v[134:137]
	v_mfma_f32_16x16x32_bf16 v[68:71], v[126:129], v[212:215], v[68:71]
	v_mfma_f32_16x16x32_bf16 v[116:119], v[140:143], v[212:215], v[116:119]
	v_mfma_f32_16x16x32_bf16 v[52:55], v[126:129], v[240:243], v[52:55]
	v_mfma_f32_16x16x32_bf16 v[112:115], v[140:143], v[240:243], v[112:115]
	s_setprio 0
	s_setprio 1
	v_mfma_f32_16x16x32_bf16 v[48:51], v[164:167], v[180:183], v[48:51]
	v_mfma_f32_16x16x32_bf16 v[16:19], v[172:175], v[180:183], v[16:19]
	v_mfma_f32_16x16x32_bf16 v[44:47], v[164:167], v[188:191], v[44:47]
	v_mfma_f32_16x16x32_bf16 v[12:15], v[172:175], v[188:191], v[12:15]
	v_mfma_f32_16x16x32_bf16 v[40:43], v[164:167], v[208:211], v[40:43]
	v_mfma_f32_16x16x32_bf16 v[8:11], v[172:175], v[208:211], v[8:11]
	v_mfma_f32_16x16x32_bf16 v[36:39], v[164:167], v[236:239], v[36:39]
	v_mfma_f32_16x16x32_bf16 v[4:7], v[172:175], v[236:239], v[4:7]
	v_mfma_f32_16x16x32_bf16 v[48:51], v[168:171], v[184:187], v[48:51]
	v_mfma_f32_16x16x32_bf16 v[16:19], v[176:179], v[184:187], v[16:19]
	v_mfma_f32_16x16x32_bf16 v[44:47], v[168:171], v[192:195], v[44:47]
	v_mfma_f32_16x16x32_bf16 v[12:15], v[176:179], v[192:195], v[12:15]
	v_mfma_f32_16x16x32_bf16 v[40:43], v[168:171], v[212:215], v[40:43]
	v_mfma_f32_16x16x32_bf16 v[8:11], v[176:179], v[212:215], v[8:11]
	v_mfma_f32_16x16x32_bf16 v[36:39], v[168:171], v[240:243], v[36:39]
	v_mfma_f32_16x16x32_bf16 v[4:7], v[176:179], v[240:243], v[4:7]
	s_setprio 0
	s_barrier
	s_add_i32 s41, 0, 0x18000
	v_add_u32_e32 v138, s41, v120
	s_add_i32 s46, 0, 0x1c000
	ds_read_b128 v[122:125], v138
	ds_read_b128 v[126:129], v138 offset:1024
	ds_read_b128 v[130:133], v138 offset:2048
	ds_read_b128 v[140:143], v138 offset:3072
	v_add_u32_e32 v138, s46, v120
	ds_read_b128 v[164:167], v138
	ds_read_b128 v[168:171], v138 offset:1024
	ds_read_b128 v[172:175], v138 offset:2048
	ds_read_b128 v[176:179], v138 offset:3072
	s_add_u32 s20, s20, s77
	s_addc_u32 s21, s21, 0
	s_mov_b32 m0, s25
	v_lshl_add_u64 v[138:139], s[20:21], 0, v[102:103]
	ds_read_b128 v[180:183], v121 offset:32768
	ds_read_b128 v[184:187], v121 offset:33792
	ds_read_b128 v[188:191], v121 offset:34816
	ds_read_b128 v[192:195], v121 offset:35840
	ds_read_b128 v[208:211], v121 offset:36864
	ds_read_b128 v[212:215], v121 offset:37888
	ds_read_b128 v[236:239], v121 offset:38912
	ds_read_b128 v[240:243], v121 offset:39936
	global_load_lds_dwordx4 v[138:139], off
	v_lshl_add_u64 v[138:139], s[20:21], 0, v[100:101]
	s_mov_b32 m0, s27
	s_nop 0
	global_load_lds_dwordx4 v[138:139], off
	s_waitcnt vmcnt(8)
	s_waitcnt lgkmcnt(0)
	s_barrier
	s_setprio 1
	s_waitcnt lgkmcnt(0)
	v_mfma_f32_16x16x32_bf16 v[96:99], v[122:125], v[180:183], v[96:99]
	v_mfma_f32_16x16x32_bf16 v[160:163], v[130:133], v[180:183], v[160:163]
	v_mfma_f32_16x16x32_bf16 v[88:91], v[122:125], v[188:191], v[88:91]
	v_mfma_f32_16x16x32_bf16 v[156:159], v[130:133], v[188:191], v[156:159]
	v_mfma_f32_16x16x32_bf16 v[92:95], v[122:125], v[208:211], v[92:95]
	v_mfma_f32_16x16x32_bf16 v[152:155], v[130:133], v[208:211], v[152:155]
	v_mfma_f32_16x16x32_bf16 v[72:75], v[122:125], v[236:239], v[72:75]
	v_mfma_f32_16x16x32_bf16 v[148:151], v[130:133], v[236:239], v[148:151]
	v_mfma_f32_16x16x32_bf16 v[96:99], v[126:129], v[184:187], v[96:99]
	v_mfma_f32_16x16x32_bf16 v[160:163], v[140:143], v[184:187], v[160:163]
	v_mfma_f32_16x16x32_bf16 v[88:91], v[126:129], v[192:195], v[88:91]
	v_mfma_f32_16x16x32_bf16 v[156:159], v[140:143], v[192:195], v[156:159]
	v_mfma_f32_16x16x32_bf16 v[92:95], v[126:129], v[212:215], v[92:95]
	v_mfma_f32_16x16x32_bf16 v[152:155], v[140:143], v[212:215], v[152:155]
	v_mfma_f32_16x16x32_bf16 v[72:75], v[126:129], v[240:243], v[72:75]
	v_mfma_f32_16x16x32_bf16 v[148:151], v[140:143], v[240:243], v[148:151]
	s_setprio 0
	s_setprio 1
	v_mfma_f32_16x16x32_bf16 v[84:87], v[164:167], v[180:183], v[84:87]
	v_mfma_f32_16x16x32_bf16 v[32:35], v[172:175], v[180:183], v[32:35]
	v_mfma_f32_16x16x32_bf16 v[76:79], v[164:167], v[188:191], v[76:79]
	v_mfma_f32_16x16x32_bf16 v[28:31], v[172:175], v[188:191], v[28:31]
	v_mfma_f32_16x16x32_bf16 v[60:63], v[164:167], v[208:211], v[60:63]
	v_mfma_f32_16x16x32_bf16 v[24:27], v[172:175], v[208:211], v[24:27]
	v_mfma_f32_16x16x32_bf16 v[56:59], v[164:167], v[236:239], v[56:59]
	v_mfma_f32_16x16x32_bf16 v[20:23], v[172:175], v[236:239], v[20:23]
	v_mfma_f32_16x16x32_bf16 v[84:87], v[168:171], v[184:187], v[84:87]
	v_mfma_f32_16x16x32_bf16 v[32:35], v[176:179], v[184:187], v[32:35]
	v_mfma_f32_16x16x32_bf16 v[76:79], v[168:171], v[192:195], v[76:79]
	v_mfma_f32_16x16x32_bf16 v[28:31], v[176:179], v[192:195], v[28:31]
	v_mfma_f32_16x16x32_bf16 v[60:63], v[168:171], v[212:215], v[60:63]
	v_mfma_f32_16x16x32_bf16 v[24:27], v[176:179], v[212:215], v[24:27]
	v_mfma_f32_16x16x32_bf16 v[56:59], v[168:171], v[240:243], v[56:59]
	v_mfma_f32_16x16x32_bf16 v[20:23], v[176:179], v[240:243], v[20:23]
	s_setprio 0
	s_barrier
; #define PG8_STAGE(bufoff, gbase, voff) do { _Pragma("unroll") for (int _i = 0; _i < 2; ++_i) \
;         __builtin_amdgcn_global_load_lds((const unsigned*)((const char*)(gbase) + (voff)[_i]), (PG8_LAS unsigned*)(lds + (bufoff) + ldsw + _i * 8192), 16, 0, 0); } while (0)
; #define PG8_LDA(dst, b, h) do { _Pragma("unroll") for (int m = 0; m < 4; ++m) _Pragma("unroll") for (int k = 0; k < 2; ++k) dst[m][k] = *(const PG8_LAS bf16x8*)(lds + PG8_SA(b, h) + aoff + m * 2048 + k * 1024); } while (0)
; #define PG8_MMA(ai, bj, At, Bt) do { __builtin_amdgcn_s_setprio(1); _Pragma("unroll") for (int m = 0; m < 4; ++m) _Pragma("unroll") for (int n = 0; n < 2; ++n) _Pragma("unroll") for (int k = 0; k < 2; ++k) \
;         acc[ai][bj][m][n] = __builtin_amdgcn_mfma_f32_16x16x32_bf16(Bt[n][k], At[m][k], acc[ai][bj][m][n], 0, 0, 0); __builtin_amdgcn_s_setprio(0); } while (0)
; #define PG8_WAIT_V(n) asm volatile("s_waitcnt vmcnt(" #n ")" ::: "memory")
; #define PG8_WAIT_L(n) asm volatile("s_waitcnt lgkmcnt(" #n ")" ::: "memory")
; #define PG8_BAR __builtin_amdgcn_s_barrier()
; #define PG8_SCHED __builtin_amdgcn_sched_barrier(0)
; template <class Epi, class Sched, bool ALIGN_EPI = false, bool SP2 = false>
; __device__ __forceinline__ void gemm_phase(PG8_LAS unsigned char* lds, const Gemm g, const Sched& S, const Epi& E) {
;     ...
;         for (int t = 0; t < nt; t += 2) {
;             const bool last = (t == nt - 2);
;             const char* a1 = cA + (size_t)(t + 1) * kstep;
;             const char* a2 = last ? nA : cA + (size_t)(t + 2) * kstep; const char* b2 = last ? nB : cB + (size_t)(t + 2) * kstep;
;             const char* a3 = a2 + kstep; const char* b3 = b2 + kstep;
;     ...
;             PG8_LDA(At, 1, 1); PG8_STAGE(PG8_SB(1, 0), b3, voffB); PG8_STAGE(PG8_SB(1, 1), b3 + hstep, voffB); PG8_STAGE(PG8_SA(1, 0), a3, voffA);
;             PG8_WAIT_V(8); PG8_WAIT_L(0); PG8_BAR; PG8_MMA(1, 0, At, B0); PG8_MMA(1, 1, At, B1); PG8_BAR; PG8_SCHED;
	s_add_i32 s20, s41, s22
	v_lshl_add_u64 v[138:139], v[204:205], 0, s[42:43]
	s_mov_b32 m0, s20
	ds_read_b128 v[180:183], v121 offset:49152
	ds_read_b128 v[184:187], v121 offset:50176
	ds_read_b128 v[188:191], v121 offset:51200
	ds_read_b128 v[192:195], v121 offset:52224
	ds_read_b128 v[208:211], v121 offset:53248
	ds_read_b128 v[212:215], v121 offset:54272
	ds_read_b128 v[236:239], v121 offset:55296
	ds_read_b128 v[240:243], v121 offset:56320
	global_load_lds_dwordx4 v[138:139], off
	v_lshl_add_u64 v[138:139], v[216:217], 0, s[42:43]
	s_add_i32 m0, s20, 0x2000
	s_add_i32 s20, s46, s22
	global_load_lds_dwordx4 v[138:139], off
	v_lshl_add_u64 v[138:139], v[244:245], 0, s[42:43]
	s_mov_b32 m0, s20
	s_nop 0
	global_load_lds_dwordx4 v[138:139], off
	v_lshl_add_u64 v[138:139], v[246:247], 0, s[42:43]
	s_add_i32 m0, s20, 0x2000
	s_nop 0
	global_load_lds_dwordx4 v[138:139], off
	v_lshl_add_u64 v[138:139], v[248:249], 0, s[42:43]
	s_mov_b32 m0, s28
	s_nop 0
	global_load_lds_dwordx4 v[138:139], off
	v_lshl_add_u64 v[138:139], v[250:251], 0, s[42:43]
	s_mov_b32 m0, s29
	s_nop 0
	global_load_lds_dwordx4 v[138:139], off
	s_waitcnt vmcnt(8)
	s_waitcnt lgkmcnt(0)
	s_barrier
	s_setprio 1
	s_waitcnt lgkmcnt(0)
	v_mfma_f32_16x16x32_bf16 v[80:83], v[122:125], v[180:183], v[80:83]
	v_mfma_f32_16x16x32_bf16 v[144:147], v[130:133], v[180:183], v[144:147]
	v_mfma_f32_16x16x32_bf16 v[64:67], v[122:125], v[188:191], v[64:67]
	v_mfma_f32_16x16x32_bf16 v[134:137], v[130:133], v[188:191], v[134:137]
	v_mfma_f32_16x16x32_bf16 v[68:71], v[122:125], v[208:211], v[68:71]
	v_mfma_f32_16x16x32_bf16 v[116:119], v[130:133], v[208:211], v[116:119]
	v_mfma_f32_16x16x32_bf16 v[52:55], v[122:125], v[236:239], v[52:55]
	v_mfma_f32_16x16x32_bf16 v[112:115], v[130:133], v[236:239], v[112:115]
	v_mfma_f32_16x16x32_bf16 v[80:83], v[126:129], v[184:187], v[80:83]
	v_mfma_f32_16x16x32_bf16 v[144:147], v[140:143], v[184:187], v[144:147]
	v_mfma_f32_16x16x32_bf16 v[64:67], v[126:129], v[192:195], v[64:67]
	v_mfma_f32_16x16x32_bf16 v[136:139], v[140:143], v[192:195], v[134:137]
	v_mfma_f32_16x16x32_bf16 v[68:71], v[126:129], v[212:215], v[68:71]
	v_mfma_f32_16x16x32_bf16 v[116:119], v[140:143], v[212:215], v[116:119]
	v_mfma_f32_16x16x32_bf16 v[52:55], v[126:129], v[240:243], v[52:55]
	v_mfma_f32_16x16x32_bf16 v[112:115], v[140:143], v[240:243], v[112:115]
	s_setprio 0
	s_setprio 1
	v_mfma_f32_16x16x32_bf16 v[48:51], v[164:167], v[180:183], v[48:51]
	v_mfma_f32_16x16x32_bf16 v[16:19], v[172:175], v[180:183], v[16:19]
	v_mfma_f32_16x16x32_bf16 v[44:47], v[164:167], v[188:191], v[44:47]
	v_mfma_f32_16x16x32_bf16 v[12:15], v[172:175], v[188:191], v[12:15]
	v_mfma_f32_16x16x32_bf16 v[40:43], v[164:167], v[208:211], v[40:43]
	v_mfma_f32_16x16x32_bf16 v[8:11], v[172:175], v[208:211], v[8:11]
	v_mfma_f32_16x16x32_bf16 v[36:39], v[164:167], v[236:239], v[36:39]
	v_mfma_f32_16x16x32_bf16 v[4:7], v[172:175], v[236:239], v[4:7]
	v_mfma_f32_16x16x32_bf16 v[48:51], v[168:171], v[184:187], v[48:51]
	v_mfma_f32_16x16x32_bf16 v[16:19], v[176:179], v[184:187], v[16:19]
	v_mfma_f32_16x16x32_bf16 v[44:47], v[168:171], v[192:195], v[44:47]
	v_mfma_f32_16x16x32_bf16 v[12:15], v[176:179], v[192:195], v[12:15]
	v_mfma_f32_16x16x32_bf16 v[40:43], v[168:171], v[212:215], v[40:43]
	v_mfma_f32_16x16x32_bf16 v[8:11], v[176:179], v[212:215], v[8:11]
	v_mfma_f32_16x16x32_bf16 v[36:39], v[168:171], v[240:243], v[36:39]
	v_mfma_f32_16x16x32_bf16 v[4:7], v[176:179], v[240:243], v[4:7]
	s_setprio 0
	s_add_u32 s18, s18, 0x100
	s_addc_u32 s19, s19, 0
	v_lshl_add_u64 v[110:111], v[110:111], 0, s[92:93]
	v_lshl_add_u64 v[108:109], v[108:109], 0, s[92:93]
	s_cmp_ge_u32 s40, s97
	s_mov_b32 s20, s40
	s_cbranch_scc1 .Lk720_exit
	s_add_i32 s40, s20, 2
	s_add_u32 s41, s12, s18
	s_addc_u32 s21, s13, s19
	s_add_u32 s46, s8, s18
	s_addc_u32 s47, s9, s19
	s_add_i32 s52, 0, 0x10000
	s_cmp_eq_u32 s78, s20
	s_cselect_b32 s21, s1, s21
	s_cselect_b32 s20, s0, s41
	s_cselect_b32 s49, s15, s47
	s_cselect_b32 s48, s14, s46
	s_add_i32 s41, 0, 0x14000
	s_barrier
	s_branch .Lk720_body
; template <class Epi, class Sched, bool ALIGN_EPI = false, bool SP2 = false>
; __device__ __forceinline__ void gemm_phase(PG8_LAS unsigned char* lds, const Gemm g, const Sched& S, const Epi& E) {
;     ...
;         if (!has_next) break;
; #pragma unroll
;         for (int a = 0; a < 2; ++a)
; #pragma unroll
;             for (int b = 0; b < 2; ++b)
; #pragma unroll
;                 for (int m = 0; m < 4; ++m)
; #pragma unroll
;                     for (int n = 0; n < 2; ++n) acc[a][b][m][n] = (f32x4){0.f, 0.f, 0.f, 0.f};
;         cur = nxt; cA = nA; cB = nB; ++ui;
.Lk720_exit:
	s_barrier
	s_and_b64 vcc, exec, s[4:5]
	s_cbranch_vccnz .LBB0_708
	v_mov_b32_e32 v4, 0
	s_mov_b32 s10, s31
	s_mov_b32 s39, s34
	s_mov_b64 s[8:9], s[14:15]
	s_mov_b64 s[12:13], s[0:1]
	s_mov_b32 s30, s35
	v_mov_b32_e32 v5, v4
	v_mov_b32_e32 v6, v4
	v_mov_b32_e32 v7, v4
	v_mov_b32_e32 v36, v4
	v_mov_b32_e32 v37, v4
	v_mov_b32_e32 v38, v4
	v_mov_b32_e32 v39, v4
	v_mov_b32_e32 v8, v4
	v_mov_b32_e32 v9, v4
	v_mov_b32_e32 v10, v4
	v_mov_b32_e32 v11, v4
	v_mov_b32_e32 v40, v4
	v_mov_b32_e32 v41, v4
	v_mov_b32_e32 v42, v4
	v_mov_b32_e32 v43, v4
	v_mov_b32_e32 v12, v4
	v_mov_b32_e32 v13, v4
	v_mov_b32_e32 v14, v4
	v_mov_b32_e32 v15, v4
	v_mov_b32_e32 v44, v4
	v_mov_b32_e32 v45, v4
	v_mov_b32_e32 v46, v4
	v_mov_b32_e32 v47, v4
	v_mov_b32_e32 v16, v4
	v_mov_b32_e32 v17, v4
	v_mov_b32_e32 v18, v4
	v_mov_b32_e32 v19, v4
	v_mov_b32_e32 v48, v4
	v_mov_b32_e32 v49, v4
	v_mov_b32_e32 v50, v4
	v_mov_b32_e32 v51, v4
	v_mov_b32_e32 v112, v4
	v_mov_b32_e32 v113, v4
	v_mov_b32_e32 v114, v4
	v_mov_b32_e32 v115, v4
	v_mov_b32_e32 v52, v4
	v_mov_b32_e32 v53, v4
	v_mov_b32_e32 v54, v4
	v_mov_b32_e32 v55, v4
	v_mov_b32_e32 v116, v4
	v_mov_b32_e32 v117, v4
	v_mov_b32_e32 v118, v4
	v_mov_b32_e32 v119, v4
	v_mov_b32_e32 v68, v4
	v_mov_b32_e32 v69, v4
	v_mov_b32_e32 v70, v4
	v_mov_b32_e32 v71, v4
	v_mov_b32_e32 v136, v4
	v_mov_b32_e32 v137, v4
	v_mov_b32_e32 v138, v4
	v_mov_b32_e32 v139, v4
	v_mov_b32_e32 v64, v4
	v_mov_b32_e32 v65, v4
	v_mov_b32_e32 v66, v4
	v_mov_b32_e32 v67, v4
	v_mov_b32_e32 v144, v4
	v_mov_b32_e32 v145, v4
	v_mov_b32_e32 v146, v4
	v_mov_b32_e32 v147, v4
	v_mov_b32_e32 v80, v4
	v_mov_b32_e32 v81, v4
	v_mov_b32_e32 v82, v4
	v_mov_b32_e32 v83, v4
	v_mov_b32_e32 v20, v4
	v_mov_b32_e32 v21, v4
	v_mov_b32_e32 v22, v4
	v_mov_b32_e32 v23, v4
	v_mov_b32_e32 v56, v4
	v_mov_b32_e32 v57, v4
	v_mov_b32_e32 v58, v4
	v_mov_b32_e32 v59, v4
	v_mov_b32_e32 v24, v4
	v_mov_b32_e32 v25, v4
	v_mov_b32_e32 v26, v4
	v_mov_b32_e32 v27, v4
	v_mov_b32_e32 v60, v4
	v_mov_b32_e32 v61, v4
	v_mov_b32_e32 v62, v4
	v_mov_b32_e32 v63, v4
	v_mov_b32_e32 v28, v4
	v_mov_b32_e32 v29, v4
	v_mov_b32_e32 v30, v4
	v_mov_b32_e32 v31, v4
	v_mov_b32_e32 v76, v4
	v_mov_b32_e32 v77, v4
	v_mov_b32_e32 v78, v4
	v_mov_b32_e32 v79, v4
	v_mov_b32_e32 v32, v4
	v_mov_b32_e32 v33, v4
	v_mov_b32_e32 v34, v4
	v_mov_b32_e32 v35, v4
	v_mov_b32_e32 v84, v4
	v_mov_b32_e32 v85, v4
	v_mov_b32_e32 v86, v4
	v_mov_b32_e32 v87, v4
	v_mov_b32_e32 v148, v4
	v_mov_b32_e32 v149, v4
	v_mov_b32_e32 v150, v4
	v_mov_b32_e32 v151, v4
	v_mov_b32_e32 v72, v4
	v_mov_b32_e32 v73, v4
	v_mov_b32_e32 v74, v4
	v_mov_b32_e32 v75, v4
	v_mov_b32_e32 v152, v4
	v_mov_b32_e32 v153, v4
	v_mov_b32_e32 v154, v4
	v_mov_b32_e32 v155, v4
	v_mov_b32_e32 v92, v4
	v_mov_b32_e32 v93, v4
	v_mov_b32_e32 v94, v4
	v_mov_b32_e32 v95, v4
	v_mov_b32_e32 v156, v4
	v_mov_b32_e32 v157, v4
	v_mov_b32_e32 v158, v4
	v_mov_b32_e32 v159, v4
	v_mov_b32_e32 v88, v4
	v_mov_b32_e32 v89, v4
	v_mov_b32_e32 v90, v4
	v_mov_b32_e32 v91, v4
	v_mov_b32_e32 v160, v4
	v_mov_b32_e32 v161, v4
	v_mov_b32_e32 v162, v4
	v_mov_b32_e32 v163, v4
	v_mov_b32_e32 v96, v4
	v_mov_b32_e32 v97, v4
	v_mov_b32_e32 v98, v4
	v_mov_b32_e32 v99, v4
	s_branch .LBB0_708

; #define PG8_STAGE(bufoff, gbase, voff) do { _Pragma("unroll") for (int _i = 0; _i < 2; ++_i) \
;         __builtin_amdgcn_global_load_lds((const unsigned*)((const char*)(gbase) + (voff)[_i]), (PG8_LAS unsigned*)(lds + (bufoff) + ldsw + _i * 8192), 16, 0, 0); } while (0)
; #define PG8_LDA(dst, b, h) do { _Pragma("unroll") for (int m = 0; m < 4; ++m) _Pragma("unroll") for (int k = 0; k < 2; ++k) dst[m][k] = *(const PG8_LAS bf16x8*)(lds + PG8_SA(b, h) + aoff + m * 2048 + k * 1024); } while (0)
; #define PG8_LDB(dst, b, h) do { _Pragma("unroll") for (int n = 0; n < 2; ++n) _Pragma("unroll") for (int k = 0; k < 2; ++k) dst[n][k] = *(const PG8_LAS bf16x8*)(lds + PG8_SB(b, h) + boff + n * 2048 + k * 1024); } while (0)
; #define PG8_MMA(ai, bj, At, Bt) do { __builtin_amdgcn_s_setprio(1); _Pragma("unroll") for (int m = 0; m < 4; ++m) _Pragma("unroll") for (int n = 0; n < 2; ++n) _Pragma("unroll") for (int k = 0; k < 2; ++k) \
;         acc[ai][bj][m][n] = __builtin_amdgcn_mfma_f32_16x16x32_bf16(Bt[n][k], At[m][k], acc[ai][bj][m][n], 0, 0, 0); __builtin_amdgcn_s_setprio(0); } while (0)
; #define PG8_WAIT_V(n) asm volatile("s_waitcnt vmcnt(" #n ")" ::: "memory")
; #define PG8_WAIT_L(n) asm volatile("s_waitcnt lgkmcnt(" #n ")" ::: "memory")
; #define PG8_BAR __builtin_amdgcn_s_barrier()
; #define PG8_SCHED __builtin_amdgcn_sched_barrier(0)
; template <class Epi, class Sched, bool ALIGN_EPI = false, bool SP2 = false>
; __device__ __forceinline__ void gemm_phase(PG8_LAS unsigned char* lds, const Gemm g, const Sched& S, const Epi& E) {
;     ...
;             PG8_LDB(B0, 0, 0); PG8_LDB(B1, 0, 1); PG8_SCHED; PG8_LDA(At, 0, 0); PG8_STAGE(PG8_SA(1, 1), a1 + hstep, voffA);
;             PG8_WAIT_V(8); PG8_WAIT_L(0); PG8_BAR; PG8_MMA(0, 0, At, B0); PG8_MMA(0, 1, At, B1); PG8_BAR; PG8_SCHED;
;             PG8_LDA(At, 0, 1); PG8_STAGE(PG8_SB(0, 0), b2, voffB); PG8_STAGE(PG8_SB(0, 1), b2 + hstep, voffB); PG8_STAGE(PG8_SA(0, 0), a2, voffA);
;             PG8_WAIT_V(8); PG8_WAIT_L(0); PG8_BAR; PG8_MMA(1, 0, At, B0); PG8_MMA(1, 1, At, B1); PG8_BAR; PG8_SCHED;
.Lk883_body:
	v_add_u32_e32 v156, s40, v141
	v_add_u32_e32 v172, s46, v141
	ds_read_b128 v[144:147], v156
	ds_read_b128 v[148:151], v156 offset:1024
	ds_read_b128 v[152:155], v156 offset:2048
	ds_read_b128 v[156:159], v156 offset:3072
	ds_read_b128 v[160:163], v172
	ds_read_b128 v[164:167], v172 offset:1024
	ds_read_b128 v[168:171], v172 offset:2048
	ds_read_b128 v[172:175], v172 offset:3072
	v_lshl_add_u64 v[216:217], s[16:17], 0, v[136:137]
	s_add_i32 m0, s23, 0xc000
	ds_read_b128 v[176:179], v143
	ds_read_b128 v[180:183], v143 offset:1024
	ds_read_b128 v[184:187], v143 offset:2048
	ds_read_b128 v[188:191], v143 offset:3072
	ds_read_b128 v[192:195], v143 offset:4096
	ds_read_b128 v[204:207], v143 offset:5120
	ds_read_b128 v[208:211], v143 offset:6144
	ds_read_b128 v[212:215], v143 offset:7168
	global_load_lds_dwordx4 v[216:217], off
	v_lshl_add_u64 v[216:217], s[16:17], 0, v[138:139]
	s_add_i32 m0, s23, 0xe000
	s_nop 0
	global_load_lds_dwordx4 v[216:217], off
	s_waitcnt vmcnt(8)
	s_waitcnt lgkmcnt(0)
	s_barrier
	s_setprio 1
	s_waitcnt lgkmcnt(0)
	v_mfma_f32_16x16x32_bf16 v[128:131], v[144:147], v[176:179], v[128:131]
	v_mfma_f32_16x16x32_bf16 v[124:127], v[152:155], v[176:179], v[124:127]
	v_mfma_f32_16x16x32_bf16 v[112:115], v[144:147], v[184:187], v[112:115]
	v_mfma_f32_16x16x32_bf16 v[108:111], v[152:155], v[184:187], v[108:111]
	v_mfma_f32_16x16x32_bf16 v[96:99], v[144:147], v[192:195], v[96:99]
	v_mfma_f32_16x16x32_bf16 v[92:95], v[152:155], v[192:195], v[92:95]
	v_mfma_f32_16x16x32_bf16 v[80:83], v[144:147], v[208:211], v[80:83]
	v_mfma_f32_16x16x32_bf16 v[76:79], v[152:155], v[208:211], v[76:79]
	v_mfma_f32_16x16x32_bf16 v[128:131], v[148:151], v[180:183], v[128:131]
	v_mfma_f32_16x16x32_bf16 v[124:127], v[156:159], v[180:183], v[124:127]
	v_mfma_f32_16x16x32_bf16 v[112:115], v[148:151], v[188:191], v[112:115]
	v_mfma_f32_16x16x32_bf16 v[108:111], v[156:159], v[188:191], v[108:111]
	v_mfma_f32_16x16x32_bf16 v[96:99], v[148:151], v[204:207], v[96:99]
	v_mfma_f32_16x16x32_bf16 v[92:95], v[156:159], v[204:207], v[92:95]
	v_mfma_f32_16x16x32_bf16 v[80:83], v[148:151], v[212:215], v[80:83]
	v_mfma_f32_16x16x32_bf16 v[76:79], v[156:159], v[212:215], v[76:79]
	s_setprio 0
	s_setprio 1
	v_mfma_f32_16x16x32_bf16 v[120:123], v[160:163], v[176:179], v[120:123]
	v_mfma_f32_16x16x32_bf16 v[116:119], v[168:171], v[176:179], v[116:119]
	v_mfma_f32_16x16x32_bf16 v[104:107], v[160:163], v[184:187], v[104:107]
	v_mfma_f32_16x16x32_bf16 v[100:103], v[168:171], v[184:187], v[100:103]
	v_mfma_f32_16x16x32_bf16 v[88:91], v[160:163], v[192:195], v[88:91]
	v_mfma_f32_16x16x32_bf16 v[84:87], v[168:171], v[192:195], v[84:87]
	v_mfma_f32_16x16x32_bf16 v[72:75], v[160:163], v[208:211], v[72:75]
	v_mfma_f32_16x16x32_bf16 v[68:71], v[168:171], v[208:211], v[68:71]
	v_mfma_f32_16x16x32_bf16 v[120:123], v[164:167], v[180:183], v[120:123]
	v_mfma_f32_16x16x32_bf16 v[116:119], v[172:175], v[180:183], v[116:119]
	v_mfma_f32_16x16x32_bf16 v[104:107], v[164:167], v[188:191], v[104:107]
	v_mfma_f32_16x16x32_bf16 v[100:103], v[172:175], v[188:191], v[100:103]
	v_mfma_f32_16x16x32_bf16 v[88:91], v[164:167], v[204:207], v[88:91]
	v_mfma_f32_16x16x32_bf16 v[84:87], v[172:175], v[204:207], v[84:87]
	v_mfma_f32_16x16x32_bf16 v[72:75], v[164:167], v[212:215], v[72:75]
	v_mfma_f32_16x16x32_bf16 v[68:71], v[172:175], v[212:215], v[68:71]
	s_setprio 0
	s_barrier
	s_add_i32 s40, s40, s22
	v_lshl_add_u64 v[216:217], s[18:19], 0, v[2:3]
	s_mov_b32 m0, s40
	ds_read_b128 v[176:179], v143 offset:16384
	ds_read_b128 v[180:183], v143 offset:17408
	ds_read_b128 v[184:187], v143 offset:18432
	ds_read_b128 v[188:191], v143 offset:19456
	ds_read_b128 v[192:195], v143 offset:20480
	ds_read_b128 v[204:207], v143 offset:21504
	ds_read_b128 v[208:211], v143 offset:22528
	ds_read_b128 v[212:215], v143 offset:23552
	global_load_lds_dwordx4 v[216:217], off
	s_add_i32 m0, s40, 0x2000
	s_add_u32 s40, s18, 0x40000
	v_lshl_add_u64 v[218:219], s[18:19], 0, v[0:1]
	s_addc_u32 s41, s19, 0
	s_add_i32 s46, s46, s22
	global_load_lds_dwordx4 v[218:219], off
	v_lshl_add_u64 v[236:237], s[40:41], 0, v[2:3]
	s_mov_b32 m0, s46
	v_lshl_add_u64 v[238:239], s[20:21], 0, v[132:133]
	global_load_lds_dwordx4 v[236:237], off
	v_lshl_add_u64 v[236:237], s[40:41], 0, v[0:1]
	s_add_i32 m0, s46, 0x2000
	s_nop 0
	global_load_lds_dwordx4 v[236:237], off
	v_lshl_add_u64 v[236:237], s[20:21], 0, v[134:135]
	s_mov_b32 m0, s23
	s_nop 0
	global_load_lds_dwordx4 v[236:237], off
	s_mov_b32 m0, s24
	s_nop 0
	global_load_lds_dwordx4 v[238:239], off
	s_waitcnt vmcnt(8)
	s_waitcnt lgkmcnt(0)
	s_barrier
; #define PG8_STAGE(bufoff, gbase, voff) do { _Pragma("unroll") for (int _i = 0; _i < 2; ++_i) \
;         __builtin_amdgcn_global_load_lds((const unsigned*)((const char*)(gbase) + (voff)[_i]), (PG8_LAS unsigned*)(lds + (bufoff) + ldsw + _i * 8192), 16, 0, 0); } while (0)
; #define PG8_LDA(dst, b, h) do { _Pragma("unroll") for (int m = 0; m < 4; ++m) _Pragma("unroll") for (int k = 0; k < 2; ++k) dst[m][k] = *(const PG8_LAS bf16x8*)(lds + PG8_SA(b, h) + aoff + m * 2048 + k * 1024); } while (0)
; #define PG8_LDB(dst, b, h) do { _Pragma("unroll") for (int n = 0; n < 2; ++n) _Pragma("unroll") for (int k = 0; k < 2; ++k) dst[n][k] = *(const PG8_LAS bf16x8*)(lds + PG8_SB(b, h) + boff + n * 2048 + k * 1024); } while (0)
; #define PG8_MMA(ai, bj, At, Bt) do { __builtin_amdgcn_s_setprio(1); _Pragma("unroll") for (int m = 0; m < 4; ++m) _Pragma("unroll") for (int n = 0; n < 2; ++n) _Pragma("unroll") for (int k = 0; k < 2; ++k) \
;         acc[ai][bj][m][n] = __builtin_amdgcn_mfma_f32_16x16x32_bf16(Bt[n][k], At[m][k], acc[ai][bj][m][n], 0, 0, 0); __builtin_amdgcn_s_setprio(0); } while (0)
; #define PG8_WAIT_V(n) asm volatile("s_waitcnt vmcnt(" #n ")" ::: "memory")
; #define PG8_WAIT_L(n) asm volatile("s_waitcnt lgkmcnt(" #n ")" ::: "memory")
; #define PG8_BAR __builtin_amdgcn_s_barrier()
; #define PG8_SCHED __builtin_amdgcn_sched_barrier(0)
; template <class Epi, class Sched, bool ALIGN_EPI = false, bool SP2 = false>
; __device__ __forceinline__ void gemm_phase(PG8_LAS unsigned char* lds, const Gemm g, const Sched& S, const Epi& E) {
;     ...
;             PG8_WAIT_V(8); PG8_WAIT_L(0); PG8_BAR; PG8_MMA(1, 0, At, B0); PG8_MMA(1, 1, At, B1); PG8_BAR; PG8_SCHED;
;             PG8_LDB(B0, 1, 0); PG8_LDB(B1, 1, 1); PG8_SCHED; PG8_LDA(At, 1, 0); PG8_STAGE(PG8_SA(0, 1), a2 + hstep, voffA);
;             PG8_WAIT_V(8); PG8_WAIT_L(0); PG8_BAR; PG8_MMA(0, 0, At, B0); PG8_MMA(0, 1, At, B1); PG8_BAR; PG8_SCHED;
	s_setprio 1
	s_waitcnt lgkmcnt(0)
	v_mfma_f32_16x16x32_bf16 v[64:67], v[144:147], v[176:179], v[64:67]
	v_mfma_f32_16x16x32_bf16 v[60:63], v[152:155], v[176:179], v[60:63]
	v_mfma_f32_16x16x32_bf16 v[48:51], v[144:147], v[184:187], v[48:51]
	v_mfma_f32_16x16x32_bf16 v[44:47], v[152:155], v[184:187], v[44:47]
	v_mfma_f32_16x16x32_bf16 v[32:35], v[144:147], v[192:195], v[32:35]
	v_mfma_f32_16x16x32_bf16 v[28:31], v[152:155], v[192:195], v[28:31]
	v_mfma_f32_16x16x32_bf16 v[16:19], v[144:147], v[208:211], v[16:19]
	v_mfma_f32_16x16x32_bf16 v[12:15], v[152:155], v[208:211], v[12:15]
	v_mfma_f32_16x16x32_bf16 v[64:67], v[148:151], v[180:183], v[64:67]
	v_mfma_f32_16x16x32_bf16 v[60:63], v[156:159], v[180:183], v[60:63]
	v_mfma_f32_16x16x32_bf16 v[48:51], v[148:151], v[188:191], v[48:51]
	v_mfma_f32_16x16x32_bf16 v[44:47], v[156:159], v[188:191], v[44:47]
	v_mfma_f32_16x16x32_bf16 v[32:35], v[148:151], v[204:207], v[32:35]
	v_mfma_f32_16x16x32_bf16 v[28:31], v[156:159], v[204:207], v[28:31]
	v_mfma_f32_16x16x32_bf16 v[16:19], v[148:151], v[212:215], v[16:19]
	v_mfma_f32_16x16x32_bf16 v[12:15], v[156:159], v[212:215], v[12:15]
	s_setprio 0
	s_setprio 1
	v_mfma_f32_16x16x32_bf16 v[56:59], v[160:163], v[176:179], v[56:59]
	v_mfma_f32_16x16x32_bf16 v[52:55], v[168:171], v[176:179], v[52:55]
	v_mfma_f32_16x16x32_bf16 v[40:43], v[160:163], v[184:187], v[40:43]
	v_mfma_f32_16x16x32_bf16 v[36:39], v[168:171], v[184:187], v[36:39]
	v_mfma_f32_16x16x32_bf16 v[24:27], v[160:163], v[192:195], v[24:27]
	v_mfma_f32_16x16x32_bf16 v[20:23], v[168:171], v[192:195], v[20:23]
	v_mfma_f32_16x16x32_bf16 v[8:11], v[160:163], v[208:211], v[8:11]
	v_mfma_f32_16x16x32_bf16 v[4:7], v[168:171], v[208:211], v[4:7]
	v_mfma_f32_16x16x32_bf16 v[56:59], v[164:167], v[180:183], v[56:59]
	v_mfma_f32_16x16x32_bf16 v[52:55], v[172:175], v[180:183], v[52:55]
	v_mfma_f32_16x16x32_bf16 v[40:43], v[164:167], v[188:191], v[40:43]
	v_mfma_f32_16x16x32_bf16 v[36:39], v[172:175], v[188:191], v[36:39]
	v_mfma_f32_16x16x32_bf16 v[24:27], v[164:167], v[204:207], v[24:27]
	v_mfma_f32_16x16x32_bf16 v[20:23], v[172:175], v[204:207], v[20:23]
	v_mfma_f32_16x16x32_bf16 v[8:11], v[164:167], v[212:215], v[8:11]
	v_mfma_f32_16x16x32_bf16 v[4:7], v[172:175], v[212:215], v[4:7]
	s_setprio 0
	s_barrier
	s_add_i32 s40, 0, 0x18000
	s_add_i32 s41, 0, 0x1c000
	v_add_u32_e32 v156, s40, v141
	v_add_u32_e32 v172, s41, v141
	ds_read_b128 v[144:147], v156
	ds_read_b128 v[148:151], v156 offset:1024
	ds_read_b128 v[152:155], v156 offset:2048
	ds_read_b128 v[156:159], v156 offset:3072
	ds_read_b128 v[160:163], v172
	ds_read_b128 v[164:167], v172 offset:1024
	ds_read_b128 v[168:171], v172 offset:2048
	ds_read_b128 v[172:175], v172 offset:3072
	s_add_u32 s20, s20, 0x40000
	s_addc_u32 s21, s21, 0
	s_mov_b32 m0, s25
	v_lshl_add_u64 v[240:241], s[20:21], 0, v[134:135]
	ds_read_b128 v[176:179], v143 offset:32768
	ds_read_b128 v[180:183], v143 offset:33792
	ds_read_b128 v[184:187], v143 offset:34816
	ds_read_b128 v[188:191], v143 offset:35840
	ds_read_b128 v[192:195], v143 offset:36864
	ds_read_b128 v[204:207], v143 offset:37888
	ds_read_b128 v[208:211], v143 offset:38912
	ds_read_b128 v[212:215], v143 offset:39936
	global_load_lds_dwordx4 v[240:241], off
	v_lshl_add_u64 v[240:241], s[20:21], 0, v[132:133]
	s_mov_b32 m0, s26
	s_nop 0
	global_load_lds_dwordx4 v[240:241], off
	s_waitcnt vmcnt(8)
	s_waitcnt lgkmcnt(0)
	s_barrier
	s_setprio 1
	s_waitcnt lgkmcnt(0)
	v_mfma_f32_16x16x32_bf16 v[128:131], v[144:147], v[176:179], v[128:131]
	v_mfma_f32_16x16x32_bf16 v[124:127], v[152:155], v[176:179], v[124:127]
	v_mfma_f32_16x16x32_bf16 v[112:115], v[144:147], v[184:187], v[112:115]
	v_mfma_f32_16x16x32_bf16 v[108:111], v[152:155], v[184:187], v[108:111]
	v_mfma_f32_16x16x32_bf16 v[96:99], v[144:147], v[192:195], v[96:99]
	v_mfma_f32_16x16x32_bf16 v[92:95], v[152:155], v[192:195], v[92:95]
	v_mfma_f32_16x16x32_bf16 v[80:83], v[144:147], v[208:211], v[80:83]
	v_mfma_f32_16x16x32_bf16 v[76:79], v[152:155], v[208:211], v[76:79]
	v_mfma_f32_16x16x32_bf16 v[128:131], v[148:151], v[180:183], v[128:131]
	v_mfma_f32_16x16x32_bf16 v[124:127], v[156:159], v[180:183], v[124:127]
	v_mfma_f32_16x16x32_bf16 v[112:115], v[148:151], v[188:191], v[112:115]
	v_mfma_f32_16x16x32_bf16 v[108:111], v[156:159], v[188:191], v[108:111]
	v_mfma_f32_16x16x32_bf16 v[96:99], v[148:151], v[204:207], v[96:99]
	v_mfma_f32_16x16x32_bf16 v[92:95], v[156:159], v[204:207], v[92:95]
	v_mfma_f32_16x16x32_bf16 v[80:83], v[148:151], v[212:215], v[80:83]
	v_mfma_f32_16x16x32_bf16 v[76:79], v[156:159], v[212:215], v[76:79]
	s_setprio 0
	s_setprio 1
	v_mfma_f32_16x16x32_bf16 v[120:123], v[160:163], v[176:179], v[120:123]
	v_mfma_f32_16x16x32_bf16 v[116:119], v[168:171], v[176:179], v[116:119]
	v_mfma_f32_16x16x32_bf16 v[104:107], v[160:163], v[184:187], v[104:107]
	v_mfma_f32_16x16x32_bf16 v[100:103], v[168:171], v[184:187], v[100:103]
	v_mfma_f32_16x16x32_bf16 v[88:91], v[160:163], v[192:195], v[88:91]
	v_mfma_f32_16x16x32_bf16 v[84:87], v[168:171], v[192:195], v[84:87]
	v_mfma_f32_16x16x32_bf16 v[72:75], v[160:163], v[208:211], v[72:75]
	v_mfma_f32_16x16x32_bf16 v[68:71], v[168:171], v[208:211], v[68:71]
	v_mfma_f32_16x16x32_bf16 v[120:123], v[164:167], v[180:183], v[120:123]
	v_mfma_f32_16x16x32_bf16 v[116:119], v[172:175], v[180:183], v[116:119]
	v_mfma_f32_16x16x32_bf16 v[104:107], v[164:167], v[188:191], v[104:107]
	v_mfma_f32_16x16x32_bf16 v[100:103], v[172:175], v[188:191], v[100:103]
	v_mfma_f32_16x16x32_bf16 v[88:91], v[164:167], v[204:207], v[88:91]
	v_mfma_f32_16x16x32_bf16 v[84:87], v[172:175], v[204:207], v[84:87]
	v_mfma_f32_16x16x32_bf16 v[72:75], v[164:167], v[212:215], v[72:75]
	v_mfma_f32_16x16x32_bf16 v[68:71], v[172:175], v[212:215], v[68:71]
	s_setprio 0
	s_barrier
; #define PG8_STAGE(bufoff, gbase, voff) do { _Pragma("unroll") for (int _i = 0; _i < 2; ++_i) \
;         __builtin_amdgcn_global_load_lds((const unsigned*)((const char*)(gbase) + (voff)[_i]), (PG8_LAS unsigned*)(lds + (bufoff) + ldsw + _i * 8192), 16, 0, 0); } while (0)
; #define PG8_LDA(dst, b, h) do { _Pragma("unroll") for (int m = 0; m < 4; ++m) _Pragma("unroll") for (int k = 0; k < 2; ++k) dst[m][k] = *(const PG8_LAS bf16x8*)(lds + PG8_SA(b, h) + aoff + m * 2048 + k * 1024); } while (0)
; #define PG8_MMA(ai, bj, At, Bt) do { __builtin_amdgcn_s_setprio(1); _Pragma("unroll") for (int m = 0; m < 4; ++m) _Pragma("unroll") for (int n = 0; n < 2; ++n) _Pragma("unroll") for (int k = 0; k < 2; ++k) \
;         acc[ai][bj][m][n] = __builtin_amdgcn_mfma_f32_16x16x32_bf16(Bt[n][k], At[m][k], acc[ai][bj][m][n], 0, 0, 0); __builtin_amdgcn_s_setprio(0); } while (0)
; #define PG8_WAIT_V(n) asm volatile("s_waitcnt vmcnt(" #n ")" ::: "memory")
; #define PG8_WAIT_L(n) asm volatile("s_waitcnt lgkmcnt(" #n ")" ::: "memory")
; #define PG8_BAR __builtin_amdgcn_s_barrier()
; #define PG8_SCHED __builtin_amdgcn_sched_barrier(0)
; template <class Epi, class Sched, bool ALIGN_EPI = false, bool SP2 = false>
; __device__ __forceinline__ void gemm_phase(PG8_LAS unsigned char* lds, const Gemm g, const Sched& S, const Epi& E) {
;     ...
;         for (int t = 0; t < nt; t += 2) {
;             const bool last = (t == nt - 2);
;             const char* a1 = cA + (size_t)(t + 1) * kstep;
;             const char* a2 = last ? nA : cA + (size_t)(t + 2) * kstep; const char* b2 = last ? nB : cB + (size_t)(t + 2) * kstep;
;             const char* a3 = a2 + kstep; const char* b3 = b2 + kstep;
;     ...
;             PG8_LDA(At, 1, 1); PG8_STAGE(PG8_SB(1, 0), b3, voffB); PG8_STAGE(PG8_SB(1, 1), b3 + hstep, voffB); PG8_STAGE(PG8_SA(1, 0), a3, voffA);
;             PG8_WAIT_V(8); PG8_WAIT_L(0); PG8_BAR; PG8_MMA(1, 0, At, B0); PG8_MMA(1, 1, At, B1); PG8_BAR; PG8_SCHED;
	s_add_i32 s20, s40, s22
	v_lshl_add_u64 v[216:217], v[216:217], 0, s[42:43]
	s_mov_b32 m0, s20
	ds_read_b128 v[176:179], v143 offset:49152
	ds_read_b128 v[180:183], v143 offset:50176
	ds_read_b128 v[184:187], v143 offset:51200
	ds_read_b128 v[188:191], v143 offset:52224
	ds_read_b128 v[192:195], v143 offset:53248
	ds_read_b128 v[204:207], v143 offset:54272
	ds_read_b128 v[208:211], v143 offset:55296
	ds_read_b128 v[212:215], v143 offset:56320
	global_load_lds_dwordx4 v[216:217], off
	s_add_i32 m0, s20, 0x2000
	s_add_u32 s18, s18, 0x40080
	v_lshl_add_u64 v[216:217], v[218:219], 0, s[42:43]
	s_addc_u32 s19, s19, 0
	s_add_i32 s20, s41, s22
	global_load_lds_dwordx4 v[216:217], off
	v_lshl_add_u64 v[216:217], s[18:19], 0, v[2:3]
	s_mov_b32 m0, s20
	s_nop 0
	global_load_lds_dwordx4 v[216:217], off
	v_lshl_add_u64 v[216:217], s[18:19], 0, v[0:1]
	s_add_i32 m0, s20, 0x2000
	s_nop 0
	global_load_lds_dwordx4 v[216:217], off
	v_lshl_add_u64 v[216:217], v[236:237], 0, s[42:43]
	s_mov_b32 m0, s27
	s_nop 0
	global_load_lds_dwordx4 v[216:217], off
	v_lshl_add_u64 v[216:217], v[238:239], 0, s[42:43]
	s_mov_b32 m0, s28
	s_nop 0
	global_load_lds_dwordx4 v[216:217], off
	s_waitcnt vmcnt(8)
	s_waitcnt lgkmcnt(0)
	s_barrier
	s_setprio 1
	s_waitcnt lgkmcnt(0)
	v_mfma_f32_16x16x32_bf16 v[64:67], v[144:147], v[176:179], v[64:67]
	v_mfma_f32_16x16x32_bf16 v[60:63], v[152:155], v[176:179], v[60:63]
	v_mfma_f32_16x16x32_bf16 v[48:51], v[144:147], v[184:187], v[48:51]
	v_mfma_f32_16x16x32_bf16 v[44:47], v[152:155], v[184:187], v[44:47]
	v_mfma_f32_16x16x32_bf16 v[32:35], v[144:147], v[192:195], v[32:35]
	v_mfma_f32_16x16x32_bf16 v[28:31], v[152:155], v[192:195], v[28:31]
	v_mfma_f32_16x16x32_bf16 v[16:19], v[144:147], v[208:211], v[16:19]
	v_mfma_f32_16x16x32_bf16 v[12:15], v[152:155], v[208:211], v[12:15]
	v_mfma_f32_16x16x32_bf16 v[64:67], v[148:151], v[180:183], v[64:67]
	v_mfma_f32_16x16x32_bf16 v[60:63], v[156:159], v[180:183], v[60:63]
	v_mfma_f32_16x16x32_bf16 v[48:51], v[148:151], v[188:191], v[48:51]
	v_mfma_f32_16x16x32_bf16 v[44:47], v[156:159], v[188:191], v[44:47]
	v_mfma_f32_16x16x32_bf16 v[32:35], v[148:151], v[204:207], v[32:35]
	v_mfma_f32_16x16x32_bf16 v[28:31], v[156:159], v[204:207], v[28:31]
	v_mfma_f32_16x16x32_bf16 v[16:19], v[148:151], v[212:215], v[16:19]
	v_mfma_f32_16x16x32_bf16 v[12:15], v[156:159], v[212:215], v[12:15]
	s_setprio 0
	s_setprio 1
	v_mfma_f32_16x16x32_bf16 v[56:59], v[160:163], v[176:179], v[56:59]
	v_mfma_f32_16x16x32_bf16 v[52:55], v[168:171], v[176:179], v[52:55]
	v_mfma_f32_16x16x32_bf16 v[40:43], v[160:163], v[184:187], v[40:43]
	v_mfma_f32_16x16x32_bf16 v[36:39], v[168:171], v[184:187], v[36:39]
	v_mfma_f32_16x16x32_bf16 v[24:27], v[160:163], v[192:195], v[24:27]
	v_mfma_f32_16x16x32_bf16 v[20:23], v[168:171], v[192:195], v[20:23]
	v_mfma_f32_16x16x32_bf16 v[8:11], v[160:163], v[208:211], v[8:11]
	v_mfma_f32_16x16x32_bf16 v[4:7], v[168:171], v[208:211], v[4:7]
	v_mfma_f32_16x16x32_bf16 v[56:59], v[164:167], v[180:183], v[56:59]
	v_mfma_f32_16x16x32_bf16 v[52:55], v[172:175], v[180:183], v[52:55]
	v_mfma_f32_16x16x32_bf16 v[40:43], v[164:167], v[188:191], v[40:43]
	v_mfma_f32_16x16x32_bf16 v[36:39], v[172:175], v[188:191], v[36:39]
	v_mfma_f32_16x16x32_bf16 v[24:27], v[164:167], v[204:207], v[24:27]
	v_mfma_f32_16x16x32_bf16 v[20:23], v[172:175], v[204:207], v[20:23]
	v_mfma_f32_16x16x32_bf16 v[8:11], v[164:167], v[212:215], v[8:11]
	v_mfma_f32_16x16x32_bf16 v[4:7], v[172:175], v[212:215], v[4:7]
	s_setprio 0
	s_add_i32 s39, s39, 2
	s_add_u32 s16, s16, 0x100
	s_addc_u32 s17, s17, 0
	s_add_u32 s35, s35, 0x100
	s_addc_u32 s38, s38, 0
	s_cmp_gt_u32 s39, 13
	s_cbranch_scc1 .Lk883_exit
	s_add_u32 s18, s16, 0xfffc0080
	s_addc_u32 s19, s17, -1
	s_add_i32 s40, 0, 0x10000
	s_cmp_eq_u32 s39, 12
	s_cselect_b32 s21, s11, s19
	s_cselect_b32 s20, s33, s18
	s_cselect_b32 s19, s9, s38
	s_cselect_b32 s18, s34, s35
	s_add_i32 s46, 0, 0x14000
	s_barrier
	s_branch .Lk883_body
.Lk883_exit:
	s_barrier
	s_and_b64 vcc, exec, s[6:7]
	s_cbranch_vccz .LBB0_886
	s_barrier
